# scan item exit: next-item atomic issued before the segment-end stores
# speedup vs baseline: 1.0114x; 1.0012x over previous
; #define LAS __attribute__((address_space(3)))
; __device__ __forceinline__ int next_item(unsigned* ctr, LAS unsigned* slot) {
;     __syncthreads();
;     if (threadIdx.x == 0) *slot = atomicAdd(ctr, 1u);
;     __syncthreads();
;     return (int)*slot;
.Lnx_a_have:
	s_waitcnt vmcnt(32)
	v_readlane_b32 s2, v254, 19
	s_nop 1
	v_mov_b32_e32 v2, s2
	s_waitcnt lgkmcnt(0)
	ds_write_b32 v2, v255
	v_mov_b32_e32 v255, -1



; #define LAS __attribute__((address_space(3)))
; __device__ __forceinline__ int crow(int r, int hi) { return (r & 3) + 8 * (r >> 2) + 4 * hi; }
; __device__ __forceinline__ void scan_pass1(const ScanP& sp, int b, int h, int seg, LAS unsigned char* lds) {
;     ...
;     if (w < 4) {
;         int le_ = lane; asm volatile("" : "+v"(le_));
;         const int ln = le_ & 31, hh = le_ >> 5, icol = 32 * (w & 1) + ln;
;         float* dst = ((w < 2) ? sp.HE : sp.PE) + (size_t)((b * 8 + h) * 4 + seg) * 4096;
; #pragma unroll
;         for (int jb = 0; jb < 2; ++jb)
; #pragma unroll
;             for (int r = 0; r < 16; ++r) dst[(32 * jb + crow(r, hh)) * 64 + icol] = Hacc[jb][r];
;     }
; __device__ __forceinline__ int next_item(unsigned* ctr, LAS unsigned* slot) {
;     __syncthreads();
;     if (threadIdx.x == 0) *slot = atomicAdd(ctr, 1u);
.LBB0_320:
	v_readlane_b32 s100, v252, 3
	v_readlane_b32 s101, v252, 4
	v_cmp_eq_u32_e32 vcc, 0, v210
	v_mov_b32_e32 v230, 1
	v_mov_b32_e32 v231, 0
	s_and_b64 vcc, vcc, exec
	s_cbranch_scc0 .Lnx_as
	s_mov_b64 exec, vcc
	global_atomic_add v255, v231, v230, s[100:101] offset:8 sc0
	s_mov_b64 exec, -1
